# m26 + index unit prologue: the 128 key registers are no longer zeroed per unit (every later read of K[jj] is guarded by jj < ntl and step A writes all of those)
# baseline (speedup 1.0000x reference)
.Lidx_pw0:
	v_cndmask_b32_e64 v19, 0, 1, s[78:79]
	v_cmp_ne_u32_e64 s[28:29], 1, v19
	s_andn2_b64 vcc, exec, s[78:79]
	v_lshlrev_b32_e32 v39, 4, v36
	v_lshlrev_b32_e32 v172, 2, v167
	v_lshl_add_u32 v40, v167, 13, 0
	v_lshl_add_u32 v41, v18, 2, s14
	s_waitcnt lgkmcnt(0)
	s_barrier
	s_cbranch_vccnz .LBB0_1383
	s_add_i32 s0, s77, 8
	s_lshr_b32 s1, s0, 29
	s_add_i32 s0, s0, s1
	s_ashr_i32 s13, s0, 3
	s_add_i32 s0, 0, 0x22200
	v_add_u32_e32 v173, s0, v39
	v_readlane_b32 s0, v251, 29
	s_add_i32 s14, s13, -2
	s_add_i32 s15, s13, -3
	v_add_u32_e32 v174, s0, v39
	s_max_i32 s0, s13, 2
	s_lshl_b32 s0, s0, 3
	s_add_i32 s0, s0, -8
	s_and_b32 s16, s0, -16
	v_or_b32_e32 v175, s24, v167
	s_add_i32 s16, s16, 16
	s_mov_b32 s17, 0
	v_mov_b32_e32 v176, v41
	s_mov_b32 s18, 0
	s_mov_b32 s19, 0
	v_lshlrev_b32_e32 v246, 21, v172
	s_branch .LBB0_1296
